# RWKV bonus term precomputed by idle scan waves; rw_finish hand-written (reads 4 streams + bonus instead of 8 streams)
# speedup vs baseline: 1.0775x; 1.0007x over previous
; __device__ __forceinline__ void unpack8(const u32x4 u, float (&f)[8]) { f[0] = bflo(u.x); f[1] = bfhi(u.x); f[2] = bflo(u.y); f[3] = bfhi(u.y); f[4] = bflo(u.z); f[5] = bfhi(u.z); f[6] = bflo(u.w); f[7] = bfhi(u.w); }
; __device__ __forceinline__ float sum8(float v) { v += dpp_mov<0xB1>(v); v += dpp_mov<0x4E>(v); v += dpp_mov<0x141>(v); return v; }
; __device__ __forceinline__ void phase_rw_finish(KP P, const Ctx& c) {
;     ...
;     for (int e = 0; e < 8; ++e) { ka8[e] = P->in[I_RWKA][ch + e]; rk8[e] = P->in[I_RWRK][ch + e]; gg8[e] = P->in[I_RWGNG][ch + e]; gb8[e] = P->in[I_RWGNB][ch + e]; }
;     u32x4 ny0, ny1, nr, nk, nv, na0, na1, ng;
;     ...
;     if (c.gw < T * 4) RF_LOAD(c.gw);
;     for (int k = c.gw; k < T * 4; k += c.ngw) { const size_t o = (size_t)(k >> 2) * D + ch;
;             float y[8]; { float ya_[8], yb_[8]; unpack8(ny0, ya_); unpack8(ny1, yb_);
; #pragma unroll
;                 for (int e = 0; e < 8; ++e) y[e] = ya_[e] + yb_[e]; }
;             float r8[8], k8[8], v8[8], a0[8], a1[8], g8[8];
;             unpack8(nr, r8); unpack8(nk, k8); unpack8(nv, v8); unpack8(na0, a0); unpack8(na1, a1); unpack8(ng, g8);
;             if (k + c.ngw < T * 4) RF_LOAD(k + c.ngw);
;             float s = 0.f;
; #pragma unroll
;             for (int e = 0; e < 8; ++e) s += y[e];
;             const float mean = sum8(s) * (1.0f / 64.0f); float q = 0.f;
; #pragma unroll
;             for (int e = 0; e < 8; ++e) { y[e] -= mean; q += y[e] * y[e]; }
;             const float rstd = rsqrtf(sum8(q) * (1.0f / 64.0f) + 64e-5f);
;             float bsum = 0.f;
; #pragma unroll
;             for (int e = 0; e < 8; ++e) { const float ka = ka8[e], rk = rk8[e];
;                 const float kd0 = k8[e] * (1.0f + (a0[e] - 1.0f) * ka), kd1 = k8[e] * (1.0f + (a1[e] - 1.0f) * ka); bsum += r8[e] * (kd0 + kd1) * rk; }
;             bsum = sum8(bsum);
.Lrw_bonus:
	s_and_b32 s60, s8, 3
	s_cmp_lg_u32 s60, 3
	s_cbranch_scc1 .LBB0_1754
	s_load_dwordx4 s[64:67], s[94:95], 0xf8
	s_load_dwordx2 s[68:69], s[94:95], 0x130
	s_lshr_b32 s61, s63, 6
	s_sub_i32 s61, s61, 4
	s_lshl_b32 s62, s2, 2
	s_add_i32 s61, s61, s62
	s_lshr_b32 s62, s8, 2
	s_lshl_b32 s62, s62, 10
	s_add_i32 s61, s61, s62
	v_and_b32_e32 v102, 63, v0
	v_lshlrev_b32_e32 v103, 6, v102
	v_lshlrev_b32_e32 v104, 7, v102
	v_lshrrev_b32_e32 v105, 1, v102
	v_lshlrev_b32_e32 v105, 2, v105
	s_waitcnt lgkmcnt(0)
	s_lshl_b32 s70, s61, 12
	s_add_u32 s72, s68, 0x67400000
	s_addc_u32 s73, s69, 0
	s_add_u32 s72, s72, s70
	s_addc_u32 s73, s73, 0
	s_add_u32 s74, s68, 0x6b800000
	s_addc_u32 s75, s69, 0
	s_add_u32 s74, s74, s70
	s_addc_u32 s75, s75, 0
	s_lshl_b32 s71, s61, 13
	s_add_u32 s76, s68, 0x56400000
	s_addc_u32 s77, s69, 0
	s_add_u32 s76, s76, s71
	s_addc_u32 s77, s77, 0
	s_add_u32 s78, s76, 0x1000
	s_addc_u32 s79, s77, 0
	global_load_dwordx4 v[38:41], v103, s[72:73]
	global_load_dwordx4 v[54:57], v103, s[74:75]
	global_load_dwordx4 v[70:73], v103, s[76:77]
	global_load_dwordx4 v[86:89], v103, s[78:79]
	global_load_dwordx4 v[42:45], v103, s[72:73] offset:16
	global_load_dwordx4 v[58:61], v103, s[74:75] offset:16
	global_load_dwordx4 v[74:77], v103, s[76:77] offset:16
	global_load_dwordx4 v[90:93], v103, s[78:79] offset:16
	global_load_dwordx4 v[46:49], v103, s[72:73] offset:32
	global_load_dwordx4 v[62:65], v103, s[74:75] offset:32
	global_load_dwordx4 v[78:81], v103, s[76:77] offset:32
	global_load_dwordx4 v[94:97], v103, s[78:79] offset:32
	global_load_dwordx4 v[50:53], v103, s[72:73] offset:48
	global_load_dwordx4 v[66:69], v103, s[74:75] offset:48
	global_load_dwordx4 v[82:85], v103, s[76:77] offset:48
	global_load_dwordx4 v[98:101], v103, s[78:79] offset:48
	global_load_dwordx4 v[170:173], v104, s[64:65]
	global_load_dwordx4 v[202:205], v104, s[66:67]
	global_load_dwordx4 v[174:177], v104, s[64:65] offset:16
	global_load_dwordx4 v[206:209], v104, s[66:67] offset:16
	global_load_dwordx4 v[178:181], v104, s[64:65] offset:32
	global_load_dwordx4 v[210:213], v104, s[66:67] offset:32
	global_load_dwordx4 v[182:185], v104, s[64:65] offset:48
	global_load_dwordx4 v[214:217], v104, s[66:67] offset:48
	global_load_dwordx4 v[186:189], v104, s[64:65] offset:64
	global_load_dwordx4 v[218:221], v104, s[66:67] offset:64
	global_load_dwordx4 v[190:193], v104, s[64:65] offset:80
	global_load_dwordx4 v[222:225], v104, s[66:67] offset:80
	global_load_dwordx4 v[194:197], v104, s[64:65] offset:96
	global_load_dwordx4 v[226:229], v104, s[66:67] offset:96
	global_load_dwordx4 v[198:201], v104, s[64:65] offset:112
	global_load_dwordx4 v[230:233], v104, s[66:67] offset:112
	v_mov_b32_e32 v106, 0
	s_lshl_b32 s70, s61, 7
	s_add_i32 s70, s70, 0x76500000
	s_add_u32 s80, s68, s70
	s_addc_u32 s81, s69, 0
	s_waitcnt vmcnt(0)
	v_lshlrev_b32_e32 v107, 16, v70
	v_lshlrev_b32_e32 v108, 16, v86
	v_lshlrev_b32_e32 v109, 16, v54
	v_lshlrev_b32_e32 v110, 16, v38
	v_add_f32_e32 v107, -1.0, v107
	v_add_f32_e32 v108, -1.0, v108
	v_fma_f32 v107, v107, v170, 1.0
	v_fma_f32 v108, v108, v170, 1.0
	v_mul_f32_e32 v107, v109, v107
	v_mul_f32_e32 v108, v109, v108
	v_add_f32_e32 v107, v107, v108
	v_mul_f32_e32 v107, v110, v107
	v_fmac_f32_e32 v106, v107, v202
	v_and_b32_e32 v107, 0xffff0000, v70
	v_and_b32_e32 v108, 0xffff0000, v86
	v_and_b32_e32 v109, 0xffff0000, v54
	v_and_b32_e32 v110, 0xffff0000, v38
	v_add_f32_e32 v107, -1.0, v107
	v_add_f32_e32 v108, -1.0, v108
	v_fma_f32 v107, v107, v171, 1.0
	v_fma_f32 v108, v108, v171, 1.0
	v_mul_f32_e32 v107, v109, v107
	v_mul_f32_e32 v108, v109, v108
	v_add_f32_e32 v107, v107, v108
	v_mul_f32_e32 v107, v110, v107
	v_fmac_f32_e32 v106, v107, v203
	v_lshlrev_b32_e32 v107, 16, v71
	v_lshlrev_b32_e32 v108, 16, v87
	v_lshlrev_b32_e32 v109, 16, v55
	v_lshlrev_b32_e32 v110, 16, v39
	v_add_f32_e32 v107, -1.0, v107
	v_add_f32_e32 v108, -1.0, v108
	v_fma_f32 v107, v107, v172, 1.0
	v_fma_f32 v108, v108, v172, 1.0
	v_mul_f32_e32 v107, v109, v107
	v_mul_f32_e32 v108, v109, v108
	v_add_f32_e32 v107, v107, v108
	v_mul_f32_e32 v107, v110, v107
	v_fmac_f32_e32 v106, v107, v204
	v_and_b32_e32 v107, 0xffff0000, v71
	v_and_b32_e32 v108, 0xffff0000, v87
	v_and_b32_e32 v109, 0xffff0000, v55
	v_and_b32_e32 v110, 0xffff0000, v39
	v_add_f32_e32 v107, -1.0, v107
	v_add_f32_e32 v108, -1.0, v108
	v_fma_f32 v107, v107, v173, 1.0
	v_fma_f32 v108, v108, v173, 1.0
	v_mul_f32_e32 v107, v109, v107
	v_mul_f32_e32 v108, v109, v108
	v_add_f32_e32 v107, v107, v108
	v_mul_f32_e32 v107, v110, v107
	v_fmac_f32_e32 v106, v107, v205
	v_lshlrev_b32_e32 v107, 16, v72
	v_lshlrev_b32_e32 v108, 16, v88
	v_lshlrev_b32_e32 v109, 16, v56
	v_lshlrev_b32_e32 v110, 16, v40
	v_add_f32_e32 v107, -1.0, v107
	v_add_f32_e32 v108, -1.0, v108
	v_fma_f32 v107, v107, v174, 1.0
	v_fma_f32 v108, v108, v174, 1.0
	v_mul_f32_e32 v107, v109, v107
	v_mul_f32_e32 v108, v109, v108
	v_add_f32_e32 v107, v107, v108
	v_mul_f32_e32 v107, v110, v107
	v_fmac_f32_e32 v106, v107, v206
	v_and_b32_e32 v107, 0xffff0000, v72
	v_and_b32_e32 v108, 0xffff0000, v88
	v_and_b32_e32 v109, 0xffff0000, v56
	v_and_b32_e32 v110, 0xffff0000, v40
	v_add_f32_e32 v107, -1.0, v107
	v_add_f32_e32 v108, -1.0, v108
	v_fma_f32 v107, v107, v175, 1.0
	v_fma_f32 v108, v108, v175, 1.0
	v_mul_f32_e32 v107, v109, v107
	v_mul_f32_e32 v108, v109, v108
	v_add_f32_e32 v107, v107, v108
	v_mul_f32_e32 v107, v110, v107
	v_fmac_f32_e32 v106, v107, v207
	v_lshlrev_b32_e32 v107, 16, v73
	v_lshlrev_b32_e32 v108, 16, v89
	v_lshlrev_b32_e32 v109, 16, v57
	v_lshlrev_b32_e32 v110, 16, v41
	v_add_f32_e32 v107, -1.0, v107
	v_add_f32_e32 v108, -1.0, v108
; __device__ __forceinline__ float sum8(float v) { v += dpp_mov<0xB1>(v); v += dpp_mov<0x4E>(v); v += dpp_mov<0x141>(v); return v; }
; __device__ __forceinline__ void phase_rw_finish(KP P, const Ctx& c) {
;     ...
;             float bsum = 0.f;
; #pragma unroll
;             for (int e = 0; e < 8; ++e) { const float ka = ka8[e], rk = rk8[e];
;                 const float kd0 = k8[e] * (1.0f + (a0[e] - 1.0f) * ka), kd1 = k8[e] * (1.0f + (a1[e] - 1.0f) * ka); bsum += r8[e] * (kd0 + kd1) * rk; }
;             bsum = sum8(bsum);
	v_fma_f32 v107, v107, v176, 1.0
	v_fma_f32 v108, v108, v176, 1.0
	v_mul_f32_e32 v107, v109, v107
	v_mul_f32_e32 v108, v109, v108
	v_add_f32_e32 v107, v107, v108
	v_mul_f32_e32 v107, v110, v107
	v_fmac_f32_e32 v106, v107, v208
	v_and_b32_e32 v107, 0xffff0000, v73
	v_and_b32_e32 v108, 0xffff0000, v89
	v_and_b32_e32 v109, 0xffff0000, v57
	v_and_b32_e32 v110, 0xffff0000, v41
	v_add_f32_e32 v107, -1.0, v107
	v_add_f32_e32 v108, -1.0, v108
	v_fma_f32 v107, v107, v177, 1.0
	v_fma_f32 v108, v108, v177, 1.0
	v_mul_f32_e32 v107, v109, v107
	v_mul_f32_e32 v108, v109, v108
	v_add_f32_e32 v107, v107, v108
	v_mul_f32_e32 v107, v110, v107
	v_fmac_f32_e32 v106, v107, v209
	v_lshlrev_b32_e32 v107, 16, v74
	v_lshlrev_b32_e32 v108, 16, v90
	v_lshlrev_b32_e32 v109, 16, v58
	v_lshlrev_b32_e32 v110, 16, v42
	v_add_f32_e32 v107, -1.0, v107
	v_add_f32_e32 v108, -1.0, v108
	v_fma_f32 v107, v107, v178, 1.0
	v_fma_f32 v108, v108, v178, 1.0
	v_mul_f32_e32 v107, v109, v107
	v_mul_f32_e32 v108, v109, v108
	v_add_f32_e32 v107, v107, v108
	v_mul_f32_e32 v107, v110, v107
	v_fmac_f32_e32 v106, v107, v210
	v_and_b32_e32 v107, 0xffff0000, v74
	v_and_b32_e32 v108, 0xffff0000, v90
	v_and_b32_e32 v109, 0xffff0000, v58
	v_and_b32_e32 v110, 0xffff0000, v42
	v_add_f32_e32 v107, -1.0, v107
	v_add_f32_e32 v108, -1.0, v108
	v_fma_f32 v107, v107, v179, 1.0
	v_fma_f32 v108, v108, v179, 1.0
	v_mul_f32_e32 v107, v109, v107
	v_mul_f32_e32 v108, v109, v108
	v_add_f32_e32 v107, v107, v108
	v_mul_f32_e32 v107, v110, v107
	v_fmac_f32_e32 v106, v107, v211
	v_lshlrev_b32_e32 v107, 16, v75
	v_lshlrev_b32_e32 v108, 16, v91
	v_lshlrev_b32_e32 v109, 16, v59
	v_lshlrev_b32_e32 v110, 16, v43
	v_add_f32_e32 v107, -1.0, v107
	v_add_f32_e32 v108, -1.0, v108
	v_fma_f32 v107, v107, v180, 1.0
	v_fma_f32 v108, v108, v180, 1.0
	v_mul_f32_e32 v107, v109, v107
	v_mul_f32_e32 v108, v109, v108
	v_add_f32_e32 v107, v107, v108
	v_mul_f32_e32 v107, v110, v107
	v_fmac_f32_e32 v106, v107, v212
	v_and_b32_e32 v107, 0xffff0000, v75
	v_and_b32_e32 v108, 0xffff0000, v91
	v_and_b32_e32 v109, 0xffff0000, v59
	v_and_b32_e32 v110, 0xffff0000, v43
	v_add_f32_e32 v107, -1.0, v107
	v_add_f32_e32 v108, -1.0, v108
	v_fma_f32 v107, v107, v181, 1.0
	v_fma_f32 v108, v108, v181, 1.0
	v_mul_f32_e32 v107, v109, v107
	v_mul_f32_e32 v108, v109, v108
	v_add_f32_e32 v107, v107, v108
	v_mul_f32_e32 v107, v110, v107
	v_fmac_f32_e32 v106, v107, v213
	v_lshlrev_b32_e32 v107, 16, v76
	v_lshlrev_b32_e32 v108, 16, v92
	v_lshlrev_b32_e32 v109, 16, v60
	v_lshlrev_b32_e32 v110, 16, v44
	v_add_f32_e32 v107, -1.0, v107
	v_add_f32_e32 v108, -1.0, v108
	v_fma_f32 v107, v107, v182, 1.0
	v_fma_f32 v108, v108, v182, 1.0
	v_mul_f32_e32 v107, v109, v107
	v_mul_f32_e32 v108, v109, v108
	v_add_f32_e32 v107, v107, v108
	v_mul_f32_e32 v107, v110, v107
	v_fmac_f32_e32 v106, v107, v214
	v_and_b32_e32 v107, 0xffff0000, v76
	v_and_b32_e32 v108, 0xffff0000, v92
	v_and_b32_e32 v109, 0xffff0000, v60
	v_and_b32_e32 v110, 0xffff0000, v44
	v_add_f32_e32 v107, -1.0, v107
	v_add_f32_e32 v108, -1.0, v108
	v_fma_f32 v107, v107, v183, 1.0
	v_fma_f32 v108, v108, v183, 1.0
	v_mul_f32_e32 v107, v109, v107
	v_mul_f32_e32 v108, v109, v108
	v_add_f32_e32 v107, v107, v108
	v_mul_f32_e32 v107, v110, v107
	v_fmac_f32_e32 v106, v107, v215
	v_lshlrev_b32_e32 v107, 16, v77
	v_lshlrev_b32_e32 v108, 16, v93
	v_lshlrev_b32_e32 v109, 16, v61
	v_lshlrev_b32_e32 v110, 16, v45
	v_add_f32_e32 v107, -1.0, v107
	v_add_f32_e32 v108, -1.0, v108
	v_fma_f32 v107, v107, v184, 1.0
	v_fma_f32 v108, v108, v184, 1.0
	v_mul_f32_e32 v107, v109, v107
	v_mul_f32_e32 v108, v109, v108
	v_add_f32_e32 v107, v107, v108
	v_mul_f32_e32 v107, v110, v107
	v_fmac_f32_e32 v106, v107, v216
	v_and_b32_e32 v107, 0xffff0000, v77
	v_and_b32_e32 v108, 0xffff0000, v93
	v_and_b32_e32 v109, 0xffff0000, v61
	v_and_b32_e32 v110, 0xffff0000, v45
	v_add_f32_e32 v107, -1.0, v107
	v_add_f32_e32 v108, -1.0, v108
	v_fma_f32 v107, v107, v185, 1.0
	v_fma_f32 v108, v108, v185, 1.0
	v_mul_f32_e32 v107, v109, v107
	v_mul_f32_e32 v108, v109, v108
	v_add_f32_e32 v107, v107, v108
	v_mul_f32_e32 v107, v110, v107
	v_fmac_f32_e32 v106, v107, v217
	v_lshlrev_b32_e32 v107, 16, v78
	v_lshlrev_b32_e32 v108, 16, v94
	v_lshlrev_b32_e32 v109, 16, v62
	v_lshlrev_b32_e32 v110, 16, v46
	v_add_f32_e32 v107, -1.0, v107
	v_add_f32_e32 v108, -1.0, v108
	v_fma_f32 v107, v107, v186, 1.0
	v_fma_f32 v108, v108, v186, 1.0
	v_mul_f32_e32 v107, v109, v107
	v_mul_f32_e32 v108, v109, v108
	v_add_f32_e32 v107, v107, v108
	v_mul_f32_e32 v107, v110, v107
	v_fmac_f32_e32 v106, v107, v218
	v_and_b32_e32 v107, 0xffff0000, v78
	v_and_b32_e32 v108, 0xffff0000, v94
	v_and_b32_e32 v109, 0xffff0000, v62
	v_and_b32_e32 v110, 0xffff0000, v46
	v_add_f32_e32 v107, -1.0, v107
	v_add_f32_e32 v108, -1.0, v108
	v_fma_f32 v107, v107, v187, 1.0
	v_fma_f32 v108, v108, v187, 1.0
	v_mul_f32_e32 v107, v109, v107
	v_mul_f32_e32 v108, v109, v108
	v_add_f32_e32 v107, v107, v108
	v_mul_f32_e32 v107, v110, v107
	v_fmac_f32_e32 v106, v107, v219
	v_lshlrev_b32_e32 v107, 16, v79
	v_lshlrev_b32_e32 v108, 16, v95
	v_lshlrev_b32_e32 v109, 16, v63
	v_lshlrev_b32_e32 v110, 16, v47
	v_add_f32_e32 v107, -1.0, v107
	v_add_f32_e32 v108, -1.0, v108
	v_fma_f32 v107, v107, v188, 1.0
	v_fma_f32 v108, v108, v188, 1.0
	v_mul_f32_e32 v107, v109, v107
	v_mul_f32_e32 v108, v109, v108
	v_add_f32_e32 v107, v107, v108
	v_mul_f32_e32 v107, v110, v107
	v_fmac_f32_e32 v106, v107, v220
	v_and_b32_e32 v107, 0xffff0000, v79
	v_and_b32_e32 v108, 0xffff0000, v95
	v_and_b32_e32 v109, 0xffff0000, v63
	v_and_b32_e32 v110, 0xffff0000, v47
	v_add_f32_e32 v107, -1.0, v107
; __device__ __forceinline__ float sum8(float v) { v += dpp_mov<0xB1>(v); v += dpp_mov<0x4E>(v); v += dpp_mov<0x141>(v); return v; }
; __device__ __forceinline__ void phase_rw_finish(KP P, const Ctx& c) {
;     ...
;             float bsum = 0.f;
; #pragma unroll
;             for (int e = 0; e < 8; ++e) { const float ka = ka8[e], rk = rk8[e];
;                 const float kd0 = k8[e] * (1.0f + (a0[e] - 1.0f) * ka), kd1 = k8[e] * (1.0f + (a1[e] - 1.0f) * ka); bsum += r8[e] * (kd0 + kd1) * rk; }
;             bsum = sum8(bsum);
	v_add_f32_e32 v108, -1.0, v108
	v_fma_f32 v107, v107, v189, 1.0
	v_fma_f32 v108, v108, v189, 1.0
	v_mul_f32_e32 v107, v109, v107
	v_mul_f32_e32 v108, v109, v108
	v_add_f32_e32 v107, v107, v108
	v_mul_f32_e32 v107, v110, v107
	v_fmac_f32_e32 v106, v107, v221
	v_lshlrev_b32_e32 v107, 16, v80
	v_lshlrev_b32_e32 v108, 16, v96
	v_lshlrev_b32_e32 v109, 16, v64
	v_lshlrev_b32_e32 v110, 16, v48
	v_add_f32_e32 v107, -1.0, v107
	v_add_f32_e32 v108, -1.0, v108
	v_fma_f32 v107, v107, v190, 1.0
	v_fma_f32 v108, v108, v190, 1.0
	v_mul_f32_e32 v107, v109, v107
	v_mul_f32_e32 v108, v109, v108
	v_add_f32_e32 v107, v107, v108
	v_mul_f32_e32 v107, v110, v107
	v_fmac_f32_e32 v106, v107, v222
	v_and_b32_e32 v107, 0xffff0000, v80
	v_and_b32_e32 v108, 0xffff0000, v96
	v_and_b32_e32 v109, 0xffff0000, v64
	v_and_b32_e32 v110, 0xffff0000, v48
	v_add_f32_e32 v107, -1.0, v107
	v_add_f32_e32 v108, -1.0, v108
	v_fma_f32 v107, v107, v191, 1.0
	v_fma_f32 v108, v108, v191, 1.0
	v_mul_f32_e32 v107, v109, v107
	v_mul_f32_e32 v108, v109, v108
	v_add_f32_e32 v107, v107, v108
	v_mul_f32_e32 v107, v110, v107
	v_fmac_f32_e32 v106, v107, v223
	v_lshlrev_b32_e32 v107, 16, v81
	v_lshlrev_b32_e32 v108, 16, v97
	v_lshlrev_b32_e32 v109, 16, v65
	v_lshlrev_b32_e32 v110, 16, v49
	v_add_f32_e32 v107, -1.0, v107
	v_add_f32_e32 v108, -1.0, v108
	v_fma_f32 v107, v107, v192, 1.0
	v_fma_f32 v108, v108, v192, 1.0
	v_mul_f32_e32 v107, v109, v107
	v_mul_f32_e32 v108, v109, v108
	v_add_f32_e32 v107, v107, v108
	v_mul_f32_e32 v107, v110, v107
	v_fmac_f32_e32 v106, v107, v224
	v_and_b32_e32 v107, 0xffff0000, v81
	v_and_b32_e32 v108, 0xffff0000, v97
	v_and_b32_e32 v109, 0xffff0000, v65
	v_and_b32_e32 v110, 0xffff0000, v49
	v_add_f32_e32 v107, -1.0, v107
	v_add_f32_e32 v108, -1.0, v108
	v_fma_f32 v107, v107, v193, 1.0
	v_fma_f32 v108, v108, v193, 1.0
	v_mul_f32_e32 v107, v109, v107
	v_mul_f32_e32 v108, v109, v108
	v_add_f32_e32 v107, v107, v108
	v_mul_f32_e32 v107, v110, v107
	v_fmac_f32_e32 v106, v107, v225
	v_lshlrev_b32_e32 v107, 16, v82
	v_lshlrev_b32_e32 v108, 16, v98
	v_lshlrev_b32_e32 v109, 16, v66
	v_lshlrev_b32_e32 v110, 16, v50
	v_add_f32_e32 v107, -1.0, v107
	v_add_f32_e32 v108, -1.0, v108
	v_fma_f32 v107, v107, v194, 1.0
	v_fma_f32 v108, v108, v194, 1.0
	v_mul_f32_e32 v107, v109, v107
	v_mul_f32_e32 v108, v109, v108
	v_add_f32_e32 v107, v107, v108
	v_mul_f32_e32 v107, v110, v107
	v_fmac_f32_e32 v106, v107, v226
	v_and_b32_e32 v107, 0xffff0000, v82
	v_and_b32_e32 v108, 0xffff0000, v98
	v_and_b32_e32 v109, 0xffff0000, v66
	v_and_b32_e32 v110, 0xffff0000, v50
	v_add_f32_e32 v107, -1.0, v107
	v_add_f32_e32 v108, -1.0, v108
	v_fma_f32 v107, v107, v195, 1.0
	v_fma_f32 v108, v108, v195, 1.0
	v_mul_f32_e32 v107, v109, v107
	v_mul_f32_e32 v108, v109, v108
	v_add_f32_e32 v107, v107, v108
	v_mul_f32_e32 v107, v110, v107
	v_fmac_f32_e32 v106, v107, v227
	v_lshlrev_b32_e32 v107, 16, v83
	v_lshlrev_b32_e32 v108, 16, v99
	v_lshlrev_b32_e32 v109, 16, v67
	v_lshlrev_b32_e32 v110, 16, v51
	v_add_f32_e32 v107, -1.0, v107
	v_add_f32_e32 v108, -1.0, v108
	v_fma_f32 v107, v107, v196, 1.0
	v_fma_f32 v108, v108, v196, 1.0
	v_mul_f32_e32 v107, v109, v107
	v_mul_f32_e32 v108, v109, v108
	v_add_f32_e32 v107, v107, v108
	v_mul_f32_e32 v107, v110, v107
	v_fmac_f32_e32 v106, v107, v228
	v_and_b32_e32 v107, 0xffff0000, v83
	v_and_b32_e32 v108, 0xffff0000, v99
	v_and_b32_e32 v109, 0xffff0000, v67
	v_and_b32_e32 v110, 0xffff0000, v51
	v_add_f32_e32 v107, -1.0, v107
	v_add_f32_e32 v108, -1.0, v108
	v_fma_f32 v107, v107, v197, 1.0
	v_fma_f32 v108, v108, v197, 1.0
	v_mul_f32_e32 v107, v109, v107
	v_mul_f32_e32 v108, v109, v108
	v_add_f32_e32 v107, v107, v108
	v_mul_f32_e32 v107, v110, v107
	v_fmac_f32_e32 v106, v107, v229
	v_lshlrev_b32_e32 v107, 16, v84
	v_lshlrev_b32_e32 v108, 16, v100
	v_lshlrev_b32_e32 v109, 16, v68
	v_lshlrev_b32_e32 v110, 16, v52
	v_add_f32_e32 v107, -1.0, v107
	v_add_f32_e32 v108, -1.0, v108
	v_fma_f32 v107, v107, v198, 1.0
	v_fma_f32 v108, v108, v198, 1.0
	v_mul_f32_e32 v107, v109, v107
	v_mul_f32_e32 v108, v109, v108
	v_add_f32_e32 v107, v107, v108
	v_mul_f32_e32 v107, v110, v107
	v_fmac_f32_e32 v106, v107, v230
	v_and_b32_e32 v107, 0xffff0000, v84
	v_and_b32_e32 v108, 0xffff0000, v100
	v_and_b32_e32 v109, 0xffff0000, v68
	v_and_b32_e32 v110, 0xffff0000, v52
	v_add_f32_e32 v107, -1.0, v107
	v_add_f32_e32 v108, -1.0, v108
	v_fma_f32 v107, v107, v199, 1.0
	v_fma_f32 v108, v108, v199, 1.0
	v_mul_f32_e32 v107, v109, v107
	v_mul_f32_e32 v108, v109, v108
	v_add_f32_e32 v107, v107, v108
	v_mul_f32_e32 v107, v110, v107
	v_fmac_f32_e32 v106, v107, v231
	v_lshlrev_b32_e32 v107, 16, v85
	v_lshlrev_b32_e32 v108, 16, v101
	v_lshlrev_b32_e32 v109, 16, v69
	v_lshlrev_b32_e32 v110, 16, v53
	v_add_f32_e32 v107, -1.0, v107
	v_add_f32_e32 v108, -1.0, v108
	v_fma_f32 v107, v107, v200, 1.0
	v_fma_f32 v108, v108, v200, 1.0
	v_mul_f32_e32 v107, v109, v107
	v_mul_f32_e32 v108, v109, v108
	v_add_f32_e32 v107, v107, v108
	v_mul_f32_e32 v107, v110, v107
	v_fmac_f32_e32 v106, v107, v232
	v_and_b32_e32 v107, 0xffff0000, v85
	v_and_b32_e32 v108, 0xffff0000, v101
	v_and_b32_e32 v109, 0xffff0000, v69
	v_and_b32_e32 v110, 0xffff0000, v53
	v_add_f32_e32 v107, -1.0, v107
	v_add_f32_e32 v108, -1.0, v108
	v_fma_f32 v107, v107, v201, 1.0
	v_fma_f32 v108, v108, v201, 1.0
	v_mul_f32_e32 v107, v109, v107
	v_mul_f32_e32 v108, v109, v108
	v_add_f32_e32 v107, v107, v108
	v_mul_f32_e32 v107, v110, v107
	v_fmac_f32_e32 v106, v107, v233
	s_nop 1
	v_add_f32_dpp v106, v106, v106 quad_perm:[1,0,3,2] row_mask:0xf bank_mask:0xf
	global_store_dword v105, v106, s[80:81]
	s_branch .LBB0_1754

; __device__ __forceinline__ void unpack8(const u32x4 u, float (&f)[8]) { f[0] = bflo(u.x); f[1] = bfhi(u.x); f[2] = bflo(u.y); f[3] = bfhi(u.y); f[4] = bflo(u.z); f[5] = bfhi(u.z); f[6] = bflo(u.w); f[7] = bfhi(u.w); }
; __device__ __forceinline__ float sum8(float v) { v += dpp_mov<0xB1>(v); v += dpp_mov<0x4E>(v); v += dpp_mov<0x141>(v); return v; }
; __device__ __forceinline__ void phase_rw_finish(KP P, const Ctx& c) {
;     ...
;     const int ch = c.lane * 8 + 512 * (c.gw & 3);
;     float ka8[8], rk8[8], gg8[8], gb8[8];
; #pragma unroll
;     for (int e = 0; e < 8; ++e) { ka8[e] = P->in[I_RWKA][ch + e]; rk8[e] = P->in[I_RWRK][ch + e]; gg8[e] = P->in[I_RWGNG][ch + e]; gb8[e] = P->in[I_RWGNB][ch + e]; }
;     u32x4 ny0, ny1, nr, nk, nv, na0, na1, ng;
;     ...
;     if (c.gw < T * 4) RF_LOAD(c.gw);
;     for (int k = c.gw; k < T * 4; k += c.ngw) { const size_t o = (size_t)(k >> 2) * D + ch;
;             float y[8]; { float ya_[8], yb_[8]; unpack8(ny0, ya_); unpack8(ny1, yb_);
; #pragma unroll
;                 for (int e = 0; e < 8; ++e) y[e] = ya_[e] + yb_[e]; }
;             float r8[8], k8[8], v8[8], a0[8], a1[8], g8[8];
;             unpack8(nr, r8); unpack8(nk, k8); unpack8(nv, v8); unpack8(na0, a0); unpack8(na1, a1); unpack8(ng, g8);
;             if (k + c.ngw < T * 4) RF_LOAD(k + c.ngw);
;             float s = 0.f;
; #pragma unroll
;             for (int e = 0; e < 8; ++e) s += y[e];
;             const float mean = sum8(s) * (1.0f / 64.0f); float q = 0.f;
; #pragma unroll
;             for (int e = 0; e < 8; ++e) { y[e] -= mean; q += y[e] * y[e]; }
;             const float rstd = rsqrtf(sum8(q) * (1.0f / 64.0f) + 64e-5f);
;             float bsum = 0.f;
; #pragma unroll
;             for (int e = 0; e < 8; ++e) { const float ka = ka8[e], rk = rk8[e];
;                 const float kd0 = k8[e] * (1.0f + (a0[e] - 1.0f) * ka), kd1 = k8[e] * (1.0f + (a1[e] - 1.0f) * ka); bsum += r8[e] * (kd0 + kd1) * rk; }
;             bsum = sum8(bsum);
;             float z[8];
; #pragma unroll
;             for (int e = 0; e < 8; ++e) z[e] = (y[e] * rstd * gg8[e] + gb8[e] + bsum * v8[e]) * g8[e];
;             *(u32x4*)(Z + o) = (u32x4){cvt_pk_bf16(z[0], z[1]), cvt_pk_bf16(z[2], z[3]), cvt_pk_bf16(z[4], z[5]), cvt_pk_bf16(z[6], z[7])}; }
.LBB0_1817:
	s_or_b64 exec, exec, s[38:39]
	s_mov_b64 s[0:1], s[94:95]
	s_waitcnt lgkmcnt(0)
	v_mov_b32_e32 v2, v0
	s_barrier
	v_readlane_b32 s40, v244, 4
	s_cmpk_lg_i32 s40, 0x100
	s_cbranch_scc1 .Lrf_orig
	s_load_dwordx4 s[44:47], s[94:95], 0x108
	s_load_dwordx2 s[48:49], s[94:95], 0x130
	v_readfirstlane_b32 s40, v0
	s_lshr_b32 s40, s40, 6
	s_lshl_b32 s41, s2, 3
	s_add_i32 s40, s40, s41
	s_and_b32 s41, s40, 3
	s_lshr_b32 s42, s40, 2
	v_and_b32_e32 v3, 63, v0
	v_lshlrev_b32_e32 v4, 4, v3
	v_lshl_add_u32 v4, s41, 10, v4
	v_lshlrev_b32_e32 v5, 1, v4
	v_lshrrev_b32_e32 v6, 3, v3
	v_lshl_add_u32 v6, s41, 3, v6
	v_lshlrev_b32_e32 v6, 2, v6
	s_waitcnt lgkmcnt(0)
	global_load_dwordx4 v[8:11], v5, s[44:45]
	global_load_dwordx4 v[12:15], v5, s[44:45] offset:16
	global_load_dwordx4 v[16:19], v5, s[46:47]
	global_load_dwordx4 v[20:23], v5, s[46:47] offset:16
	s_lshl_b32 s43, s42, 12
	s_add_u32 s50, s48, 0x3cc00000
	s_addc_u32 s51, s49, 0
	s_add_u32 s50, s50, s43
	s_addc_u32 s51, s51, 0
	s_add_u32 s52, s48, 0x45400000
	s_addc_u32 s53, s49, 0
	s_add_u32 s52, s52, s43
	s_addc_u32 s53, s53, 0
	s_add_u32 s54, s48, 0x6fc00000
	s_addc_u32 s55, s49, 0
	s_add_u32 s54, s54, s43
	s_addc_u32 s55, s55, 0
	s_add_u32 s56, s48, 0x5ec00000
	s_addc_u32 s57, s49, 0
	s_add_u32 s56, s56, s43
	s_addc_u32 s57, s57, 0
	s_add_u32 s58, s48, 0x38800000
	s_addc_u32 s59, s49, 0
	s_add_u32 s58, s58, s43
	s_addc_u32 s59, s59, 0
	s_lshl_b32 s43, s42, 7
	s_add_u32 s60, s48, 0x76500000
	s_addc_u32 s61, s49, 0
	s_add_u32 s60, s60, s43
	s_addc_u32 s61, s61, 0
	global_load_dwordx4 v[24:27], v4, s[50:51]
	global_load_dwordx4 v[28:31], v4, s[52:53]
	global_load_dwordx4 v[32:35], v4, s[54:55]
	global_load_dwordx4 v[36:39], v4, s[56:57]
	global_load_dword v40, v6, s[60:61]
	s_add_u32 s50, s50, 0x200000
	s_addc_u32 s51, s51, 0
	s_add_u32 s52, s52, 0x200000
	s_addc_u32 s53, s53, 0
	s_add_u32 s54, s54, 0x200000
	s_addc_u32 s55, s55, 0
	s_add_u32 s56, s56, 0x200000
	s_addc_u32 s57, s57, 0
	s_add_u32 s60, s60, 0x10000
	s_addc_u32 s61, s61, 0
	global_load_dwordx4 v[44:47], v4, s[50:51]
	global_load_dwordx4 v[48:51], v4, s[52:53]
	global_load_dwordx4 v[52:55], v4, s[54:55]
	global_load_dwordx4 v[56:59], v4, s[56:57]
	global_load_dword v60, v6, s[60:61]
	s_add_u32 s50, s50, 0x200000
	s_addc_u32 s51, s51, 0
	s_add_u32 s52, s52, 0x200000
	s_addc_u32 s53, s53, 0
	s_add_u32 s54, s54, 0x200000
	s_addc_u32 s55, s55, 0
	s_add_u32 s56, s56, 0x200000
	s_addc_u32 s57, s57, 0
	s_add_u32 s60, s60, 0x10000
	s_addc_u32 s61, s61, 0
	s_mov_b32 s62, 0
	v_mov_b32_e32 v7, 0x3c800000
.Lrf_loop:
	s_waitcnt vmcnt(5)
	v_lshlrev_b32_e32 v64, 16, v24
	v_lshlrev_b32_e32 v72, 16, v28
	v_and_b32_e32 v65, 0xffff0000, v24
	v_and_b32_e32 v73, 0xffff0000, v28
	v_lshlrev_b32_e32 v66, 16, v25
	v_lshlrev_b32_e32 v74, 16, v29
	v_and_b32_e32 v67, 0xffff0000, v25
	v_and_b32_e32 v75, 0xffff0000, v29
	v_lshlrev_b32_e32 v68, 16, v26
	v_lshlrev_b32_e32 v76, 16, v30
	v_and_b32_e32 v69, 0xffff0000, v26
	v_and_b32_e32 v77, 0xffff0000, v30
	v_lshlrev_b32_e32 v70, 16, v27
	v_lshlrev_b32_e32 v78, 16, v31
	v_and_b32_e32 v71, 0xffff0000, v27
	v_and_b32_e32 v79, 0xffff0000, v31
	v_add_f32_e32 v64, v64, v72
	v_add_f32_e32 v65, v65, v73
	v_add_f32_e32 v66, v66, v74
	v_add_f32_e32 v67, v67, v75
	v_add_f32_e32 v68, v68, v76
	v_add_f32_e32 v69, v69, v77
	v_add_f32_e32 v70, v70, v78
	v_add_f32_e32 v71, v71, v79
	v_add_f32_e32 v88, v64, v65
	v_add_f32_e32 v88, v88, v66
	v_add_f32_e32 v88, v88, v67
	v_add_f32_e32 v88, v88, v68
	v_add_f32_e32 v88, v88, v69
	v_add_f32_e32 v88, v88, v70
	v_add_f32_e32 v88, v88, v71
	v_lshlrev_b32_e32 v72, 16, v32
	v_lshlrev_b32_e32 v80, 16, v36
	v_add_f32_dpp v88, v88, v88 quad_perm:[1,0,3,2] row_mask:0xf bank_mask:0xf
	v_and_b32_e32 v73, 0xffff0000, v32
	v_and_b32_e32 v81, 0xffff0000, v36
	v_add_f32_dpp v88, v88, v88 quad_perm:[2,3,0,1] row_mask:0xf bank_mask:0xf
	v_lshlrev_b32_e32 v74, 16, v33
	v_lshlrev_b32_e32 v82, 16, v37
	v_add_f32_dpp v88, v88, v88 row_half_mirror row_mask:0xf bank_mask:0xf
	v_mul_f32_e32 v88, v88, v7
	v_sub_f32_e32 v64, v64, v88
	v_sub_f32_e32 v65, v65, v88
	v_sub_f32_e32 v66, v66, v88
	v_sub_f32_e32 v67, v67, v88
	v_sub_f32_e32 v68, v68, v88
	v_sub_f32_e32 v69, v69, v88
	v_sub_f32_e32 v70, v70, v88
	v_sub_f32_e32 v71, v71, v88
	v_mul_f32_e32 v89, v64, v64
	v_fmac_f32_e32 v89, v65, v65
	v_fmac_f32_e32 v89, v66, v66
	v_fmac_f32_e32 v89, v67, v67
	v_fmac_f32_e32 v89, v68, v68
	v_fmac_f32_e32 v89, v69, v69
	v_fmac_f32_e32 v89, v70, v70
	v_fmac_f32_e32 v89, v71, v71
	v_and_b32_e32 v75, 0xffff0000, v33
	v_and_b32_e32 v83, 0xffff0000, v37
	v_add_f32_dpp v89, v89, v89 quad_perm:[1,0,3,2] row_mask:0xf bank_mask:0xf
	v_lshlrev_b32_e32 v76, 16, v34
	v_lshlrev_b32_e32 v84, 16, v38
	v_add_f32_dpp v89, v89, v89 quad_perm:[2,3,0,1] row_mask:0xf bank_mask:0xf
	v_and_b32_e32 v77, 0xffff0000, v34
	v_and_b32_e32 v85, 0xffff0000, v38
	v_add_f32_dpp v89, v89, v89 row_half_mirror row_mask:0xf bank_mask:0xf
	v_lshlrev_b32_e32 v78, 16, v35
	v_lshlrev_b32_e32 v86, 16, v39
	v_and_b32_e32 v79, 0xffff0000, v35
	v_and_b32_e32 v87, 0xffff0000, v39
	v_mov_b32_e32 v90, 0x3a27c5ac
	v_fmac_f32_e32 v90, v89, v7
	v_rsq_f32_e32 v90, v90
	s_nop 0
	v_mul_f32_e32 v64, v64, v90
	v_mul_f32_e32 v65, v65, v90
	v_mul_f32_e32 v66, v66, v90
	v_mul_f32_e32 v67, v67, v90
	v_mul_f32_e32 v68, v68, v90
	v_mul_f32_e32 v69, v69, v90
	v_mul_f32_e32 v70, v70, v90
	v_mul_f32_e32 v71, v71, v90
	v_fma_f32 v64, v64, v8, v16
	v_fma_f32 v65, v65, v9, v17
	v_fma_f32 v66, v66, v10, v18
	v_fma_f32 v67, v67, v11, v19
	v_fma_f32 v68, v68, v12, v20
	v_fma_f32 v69, v69, v13, v21
	v_fma_f32 v70, v70, v14, v22
	v_fma_f32 v71, v71, v15, v23
	v_fmac_f32_e32 v64, v40, v72
	v_fmac_f32_e32 v65, v40, v73
	v_fmac_f32_e32 v66, v40, v74
	v_fmac_f32_e32 v67, v40, v75
	v_fmac_f32_e32 v68, v40, v76
	v_fmac_f32_e32 v69, v40, v77
	v_fmac_f32_e32 v70, v40, v78
	v_fmac_f32_e32 v71, v40, v79
	v_mul_f32_e32 v64, v64, v80
	v_mul_f32_e32 v65, v65, v81
	v_mul_f32_e32 v66, v66, v82
	v_mul_f32_e32 v67, v67, v83
	v_mul_f32_e32 v68, v68, v84
	v_mul_f32_e32 v69, v69, v85
	v_mul_f32_e32 v70, v70, v86
	v_mul_f32_e32 v71, v71, v87
	v_cvt_pk_bf16_f32 v92, v64, v65
	v_cvt_pk_bf16_f32 v93, v66, v67
	v_cvt_pk_bf16_f32 v94, v68, v69
	v_cvt_pk_bf16_f32 v95, v70, v71
	global_store_dwordx4 v4, v[92:95], s[58:59]
	s_add_u32 s58, s58, 0x200000
	s_addc_u32 s59, s59, 0
	global_load_dwordx4 v[24:27], v4, s[50:51]
	global_load_dwordx4 v[28:31], v4, s[52:53]
	global_load_dwordx4 v[32:35], v4, s[54:55]
	global_load_dwordx4 v[36:39], v4, s[56:57]
	global_load_dword v40, v6, s[60:61]
	s_add_u32 s50, s50, 0x200000
	s_addc_u32 s51, s51, 0
	s_add_u32 s52, s52, 0x200000
	s_addc_u32 s53, s53, 0
	s_add_u32 s54, s54, 0x200000
	s_addc_u32 s55, s55, 0
	s_add_u32 s56, s56, 0x200000
	s_addc_u32 s57, s57, 0
	s_add_u32 s60, s60, 0x10000
	s_addc_u32 s61, s61, 0
	s_waitcnt vmcnt(5)
; __device__ __forceinline__ void unpack8(const u32x4 u, float (&f)[8]) { f[0] = bflo(u.x); f[1] = bfhi(u.x); f[2] = bflo(u.y); f[3] = bfhi(u.y); f[4] = bflo(u.z); f[5] = bfhi(u.z); f[6] = bflo(u.w); f[7] = bfhi(u.w); }
; __device__ __forceinline__ float sum8(float v) { v += dpp_mov<0xB1>(v); v += dpp_mov<0x4E>(v); v += dpp_mov<0x141>(v); return v; }
; __device__ __forceinline__ void phase_rw_finish(KP P, const Ctx& c) {
;     ...
;     for (int k = c.gw; k < T * 4; k += c.ngw) { const size_t o = (size_t)(k >> 2) * D + ch;
;             float y[8]; { float ya_[8], yb_[8]; unpack8(ny0, ya_); unpack8(ny1, yb_);
; #pragma unroll
;                 for (int e = 0; e < 8; ++e) y[e] = ya_[e] + yb_[e]; }
;             float r8[8], k8[8], v8[8], a0[8], a1[8], g8[8];
;             unpack8(nr, r8); unpack8(nk, k8); unpack8(nv, v8); unpack8(na0, a0); unpack8(na1, a1); unpack8(ng, g8);
;             if (k + c.ngw < T * 4) RF_LOAD(k + c.ngw);
;             float s = 0.f;
; #pragma unroll
;             for (int e = 0; e < 8; ++e) s += y[e];
;             const float mean = sum8(s) * (1.0f / 64.0f); float q = 0.f;
; #pragma unroll
;             for (int e = 0; e < 8; ++e) { y[e] -= mean; q += y[e] * y[e]; }
;             const float rstd = rsqrtf(sum8(q) * (1.0f / 64.0f) + 64e-5f);
;             float bsum = 0.f;
; #pragma unroll
;             for (int e = 0; e < 8; ++e) { const float ka = ka8[e], rk = rk8[e];
;                 const float kd0 = k8[e] * (1.0f + (a0[e] - 1.0f) * ka), kd1 = k8[e] * (1.0f + (a1[e] - 1.0f) * ka); bsum += r8[e] * (kd0 + kd1) * rk; }
;             bsum = sum8(bsum);
;             float z[8];
; #pragma unroll
;             for (int e = 0; e < 8; ++e) z[e] = (y[e] * rstd * gg8[e] + gb8[e] + bsum * v8[e]) * g8[e];
;             *(u32x4*)(Z + o) = (u32x4){cvt_pk_bf16(z[0], z[1]), cvt_pk_bf16(z[2], z[3]), cvt_pk_bf16(z[4], z[5]), cvt_pk_bf16(z[6], z[7])}; }
	v_lshlrev_b32_e32 v64, 16, v44
	v_lshlrev_b32_e32 v72, 16, v48
	v_and_b32_e32 v65, 0xffff0000, v44
	v_and_b32_e32 v73, 0xffff0000, v48
	v_lshlrev_b32_e32 v66, 16, v45
	v_lshlrev_b32_e32 v74, 16, v49
	v_and_b32_e32 v67, 0xffff0000, v45
	v_and_b32_e32 v75, 0xffff0000, v49
	v_lshlrev_b32_e32 v68, 16, v46
	v_lshlrev_b32_e32 v76, 16, v50
	v_and_b32_e32 v69, 0xffff0000, v46
	v_and_b32_e32 v77, 0xffff0000, v50
	v_lshlrev_b32_e32 v70, 16, v47
	v_lshlrev_b32_e32 v78, 16, v51
	v_and_b32_e32 v71, 0xffff0000, v47
	v_and_b32_e32 v79, 0xffff0000, v51
	v_add_f32_e32 v64, v64, v72
	v_add_f32_e32 v65, v65, v73
	v_add_f32_e32 v66, v66, v74
	v_add_f32_e32 v67, v67, v75
	v_add_f32_e32 v68, v68, v76
	v_add_f32_e32 v69, v69, v77
	v_add_f32_e32 v70, v70, v78
	v_add_f32_e32 v71, v71, v79
	v_add_f32_e32 v88, v64, v65
	v_add_f32_e32 v88, v88, v66
	v_add_f32_e32 v88, v88, v67
	v_add_f32_e32 v88, v88, v68
	v_add_f32_e32 v88, v88, v69
	v_add_f32_e32 v88, v88, v70
	v_add_f32_e32 v88, v88, v71
	v_lshlrev_b32_e32 v72, 16, v52
	v_lshlrev_b32_e32 v80, 16, v56
	v_add_f32_dpp v88, v88, v88 quad_perm:[1,0,3,2] row_mask:0xf bank_mask:0xf
	v_and_b32_e32 v73, 0xffff0000, v52
	v_and_b32_e32 v81, 0xffff0000, v56
	v_add_f32_dpp v88, v88, v88 quad_perm:[2,3,0,1] row_mask:0xf bank_mask:0xf
	v_lshlrev_b32_e32 v74, 16, v53
	v_lshlrev_b32_e32 v82, 16, v57
	v_add_f32_dpp v88, v88, v88 row_half_mirror row_mask:0xf bank_mask:0xf
	v_mul_f32_e32 v88, v88, v7
	v_sub_f32_e32 v64, v64, v88
	v_sub_f32_e32 v65, v65, v88
	v_sub_f32_e32 v66, v66, v88
	v_sub_f32_e32 v67, v67, v88
	v_sub_f32_e32 v68, v68, v88
	v_sub_f32_e32 v69, v69, v88
	v_sub_f32_e32 v70, v70, v88
	v_sub_f32_e32 v71, v71, v88
	v_mul_f32_e32 v89, v64, v64
	v_fmac_f32_e32 v89, v65, v65
	v_fmac_f32_e32 v89, v66, v66
	v_fmac_f32_e32 v89, v67, v67
	v_fmac_f32_e32 v89, v68, v68
	v_fmac_f32_e32 v89, v69, v69
	v_fmac_f32_e32 v89, v70, v70
	v_fmac_f32_e32 v89, v71, v71
	v_and_b32_e32 v75, 0xffff0000, v53
	v_and_b32_e32 v83, 0xffff0000, v57
	v_add_f32_dpp v89, v89, v89 quad_perm:[1,0,3,2] row_mask:0xf bank_mask:0xf
	v_lshlrev_b32_e32 v76, 16, v54
	v_lshlrev_b32_e32 v84, 16, v58
	v_add_f32_dpp v89, v89, v89 quad_perm:[2,3,0,1] row_mask:0xf bank_mask:0xf
	v_and_b32_e32 v77, 0xffff0000, v54
	v_and_b32_e32 v85, 0xffff0000, v58
	v_add_f32_dpp v89, v89, v89 row_half_mirror row_mask:0xf bank_mask:0xf
	v_lshlrev_b32_e32 v78, 16, v55
	v_lshlrev_b32_e32 v86, 16, v59
	v_and_b32_e32 v79, 0xffff0000, v55
	v_and_b32_e32 v87, 0xffff0000, v59
	v_mov_b32_e32 v90, 0x3a27c5ac
	v_fmac_f32_e32 v90, v89, v7
	v_rsq_f32_e32 v90, v90
	s_nop 0
	v_mul_f32_e32 v64, v64, v90
	v_mul_f32_e32 v65, v65, v90
	v_mul_f32_e32 v66, v66, v90
	v_mul_f32_e32 v67, v67, v90
	v_mul_f32_e32 v68, v68, v90
	v_mul_f32_e32 v69, v69, v90
	v_mul_f32_e32 v70, v70, v90
	v_mul_f32_e32 v71, v71, v90
	v_fma_f32 v64, v64, v8, v16
	v_fma_f32 v65, v65, v9, v17
	v_fma_f32 v66, v66, v10, v18
	v_fma_f32 v67, v67, v11, v19
	v_fma_f32 v68, v68, v12, v20
	v_fma_f32 v69, v69, v13, v21
	v_fma_f32 v70, v70, v14, v22
	v_fma_f32 v71, v71, v15, v23
	v_fmac_f32_e32 v64, v60, v72
	v_fmac_f32_e32 v65, v60, v73
	v_fmac_f32_e32 v66, v60, v74
	v_fmac_f32_e32 v67, v60, v75
	v_fmac_f32_e32 v68, v60, v76
	v_fmac_f32_e32 v69, v60, v77
	v_fmac_f32_e32 v70, v60, v78
	v_fmac_f32_e32 v71, v60, v79
	v_mul_f32_e32 v64, v64, v80
	v_mul_f32_e32 v65, v65, v81
	v_mul_f32_e32 v66, v66, v82
	v_mul_f32_e32 v67, v67, v83
	v_mul_f32_e32 v68, v68, v84
	v_mul_f32_e32 v69, v69, v85
	v_mul_f32_e32 v70, v70, v86
	v_mul_f32_e32 v71, v71, v87
	v_cvt_pk_bf16_f32 v92, v64, v65
	v_cvt_pk_bf16_f32 v93, v66, v67
	v_cvt_pk_bf16_f32 v94, v68, v69
	v_cvt_pk_bf16_f32 v95, v70, v71
	global_store_dwordx4 v4, v[92:95], s[58:59]
	s_add_u32 s58, s58, 0x200000
	s_addc_u32 s59, s59, 0
	global_load_dwordx4 v[44:47], v4, s[50:51]
	global_load_dwordx4 v[48:51], v4, s[52:53]
	global_load_dwordx4 v[52:55], v4, s[54:55]
	global_load_dwordx4 v[56:59], v4, s[56:57]
	global_load_dword v60, v6, s[60:61]
	s_add_u32 s50, s50, 0x200000
	s_addc_u32 s51, s51, 0
	s_add_u32 s52, s52, 0x200000
	s_addc_u32 s53, s53, 0
	s_add_u32 s54, s54, 0x200000
	s_addc_u32 s55, s55, 0
	s_add_u32 s56, s56, 0x200000
	s_addc_u32 s57, s57, 0
	s_add_u32 s60, s60, 0x10000
	s_addc_u32 s61, s61, 0
	s_add_i32 s62, s62, 1
	s_cmp_lt_u32 s62, 17
	s_cbranch_scc1 .Lrf_loop
	s_branch .Lrf_done
; __device__ __forceinline__ void phase_rw_finish(KP P, const Ctx& c) {
;     ...
;     const int ch = c.lane * 8 + 512 * (c.gw & 3);
;     float ka8[8], rk8[8], gg8[8], gb8[8];
; #pragma unroll
;     for (int e = 0; e < 8; ++e) { ka8[e] = P->in[I_RWKA][ch + e]; rk8[e] = P->in[I_RWRK][ch + e]; gg8[e] = P->in[I_RWGNG][ch + e]; gb8[e] = P->in[I_RWGNB][ch + e]; }
;     u32x4 ny0, ny1, nr, nk, nv, na0, na1, ng;
;     ...
;     if (c.gw < T * 4) RF_LOAD(c.gw);
.Lrf_orig:
	s_nop 0
	v_readfirstlane_b32 s3, v2
	s_ashr_i32 s4, s3, 6
	v_readlane_b32 s3, v239, 11
	s_add_i32 s3, s4, s3
	s_cmp_lt_i32 s3, 0x11000
	s_cbranch_scc0 .LBB0_1822
	s_load_dwordx8 s[44:51], s[0:1], 0xf8
	s_load_dwordx2 s[54:55], s[0:1], 0x130
	v_lshlrev_b32_e32 v2, 3, v2
	v_and_b32_e32 v2, 0x1f8, v2
	v_mov_b32_e32 v99, 0
	v_mov_b32_e32 v102, 0x3a27c5ac
	s_waitcnt lgkmcnt(0)
	s_add_u32 s38, s54, 0x67400000
	s_addc_u32 s39, s55, 0
	s_add_u32 s40, s54, 0x6fc00000
	s_addc_u32 s41, s55, 0
	s_add_u32 s42, s54, 0x5ec00000
	s_addc_u32 s43, s55, 0
	s_add_u32 s52, s54, 0x45400000
	s_addc_u32 s53, s55, 0
	s_lshl_b32 s0, s4, 9
	s_and_b32 s0, s0, 0x600
	s_waitcnt vmcnt(1)
	v_or_b32_e32 v34, s0, v2
	v_lshlrev_b32_e32 v30, 2, v34
	global_load_dwordx4 v[2:5], v30, s[44:45] offset:16
	global_load_dwordx4 v[6:9], v30, s[44:45]
	global_load_dwordx4 v[10:13], v30, s[46:47] offset:16
	global_load_dwordx4 v[14:17], v30, s[46:47]
	global_load_dwordx4 v[18:21], v30, s[48:49] offset:16
	global_load_dwordx4 v[22:25], v30, s[48:49]
	global_load_dwordx4 v[26:29], v30, s[50:51] offset:16
	s_nop 0
	global_load_dwordx4 v[30:33], v30, s[50:51]
	s_add_u32 s44, s54, 0x6b800000
	s_addc_u32 s45, s55, 0
	s_add_u32 s0, s54, 0x56400000
	s_addc_u32 s1, s55, 0
	s_add_u32 s46, s54, 0x3cc00000
	s_addc_u32 s47, s55, 0
	s_ashr_i32 s4, s3, 2
	s_ashr_i32 s5, s4, 31
	s_lshl_b64 s[8:9], s[4:5], 12
	v_lshlrev_b32_e32 v98, 1, v34
	v_or_b32_e32 v36, s8, v98
	v_mov_b32_e32 v37, s9
	v_lshl_add_u64 v[38:39], s[46:47], 0, v[36:37]
	global_load_dwordx4 v[50:53], v[38:39], off
	v_lshl_add_u64 v[38:39], s[52:53], 0, v[36:37]
	global_load_dwordx4 v[58:61], v[38:39], off
	v_lshl_add_u64 v[38:39], s[38:39], 0, v[36:37]
	s_lshl_b64 s[4:5], s[4:5], 13
	global_load_dwordx4 v[94:97], v[38:39], off
	v_lshl_add_u64 v[38:39], s[44:45], 0, v[36:37]
	s_add_u32 s4, s0, s4
	global_load_dwordx4 v[90:93], v[38:39], off
	v_lshl_add_u64 v[38:39], s[40:41], 0, v[36:37]
	s_addc_u32 s5, s1, s5
	v_lshl_add_u64 v[36:37], s[42:43], 0, v[36:37]
	global_load_dwordx4 v[66:69], v[38:39], off
	v_lshl_add_u64 v[38:39], s[4:5], 0, v[98:99]
	global_load_dwordx4 v[82:85], v98, s[4:5]
	global_load_dwordx4 v[78:81], v[36:37], off
	s_movk_i32 s4, 0x1000
	v_add_co_u32_e32 v38, vcc, s4, v38
	v_lshl_add_u64 v[36:37], s[54:55], 0, v[98:99]
	s_nop 0
	v_addc_co_u32_e32 v39, vcc, 0, v39, vcc
	global_load_dwordx4 v[86:89], v[38:39], off
	s_mov_b64 s[4:5], 0x38800000
	v_lshl_add_u64 v[100:101], v[36:37], 0, s[4:5]
	v_lshlrev_b32_e32 v98, 1, v34
	s_waitcnt vmcnt(7)
	v_mov_b64_e32 v[34:35], v[50:51]
	v_mov_b64_e32 v[36:37], v[52:53]
	s_waitcnt vmcnt(6)
	v_mov_b64_e32 v[38:39], v[58:59]
	v_mov_b64_e32 v[40:41], v[60:61]
	s_waitcnt vmcnt(5)
	v_mov_b64_e32 v[42:43], v[94:95]
	v_mov_b64_e32 v[44:45], v[96:97]
	s_waitcnt vmcnt(4)
	v_mov_b64_e32 v[46:47], v[90:91]
	v_mov_b64_e32 v[48:49], v[92:93]
	s_waitcnt vmcnt(3)
	v_mov_b64_e32 v[54:55], v[66:67]
	v_mov_b64_e32 v[56:57], v[68:69]
	s_waitcnt vmcnt(2)
	v_mov_b64_e32 v[62:63], v[82:83]
	s_waitcnt vmcnt(1)
	v_mov_b64_e32 v[74:75], v[78:79]
	v_mov_b64_e32 v[76:77], v[80:81]
	v_mov_b64_e32 v[64:65], v[84:85]
	s_waitcnt vmcnt(0)
	v_mov_b64_e32 v[70:71], v[86:87]
	v_mov_b64_e32 v[72:73], v[88:89]
	s_branch .LBB0_1820

; __device__ __forceinline__ void xcd_barrier(const XcdBarrier& b) {
;     asm volatile("s_waitcnt vmcnt(0)" ::: "memory");
;     __syncthreads();
;     if (threadIdx.x == 0) {
;         unsigned* bar = b.bar;
;         __builtin_amdgcn_s_waitcnt(0);
;         unsigned nloc = b.st[0], nx = b.st[1];
;         if (nloc == 0u) { xcd_barrier_complete(bar, b.x, nloc, nx); b.st[0] = nloc; b.st[1] = nx; }
.LBB0_1822:
.Lrf_done:
	s_waitcnt vmcnt(0)
	s_barrier
	s_mov_b64 s[38:39], exec
	v_readlane_b32 s0, v244, 0
	v_readlane_b32 s1, v244, 1
	s_and_b64 s[0:1], s[38:39], s[0:1]
	s_mov_b64 exec, s[0:1]
	s_cbranch_execz .LBB0_1874
	s_add_i32 s0, 0, 0x23f20
	v_mov_b32_e32 v2, s0
	s_waitcnt vmcnt(0) expcnt(0) lgkmcnt(0)
	ds_read_b32 v4, v2
	s_add_i32 s0, 0, 0x23f24
	v_mov_b32_e32 v2, s0
	ds_read_b32 v2, v2
	s_waitcnt lgkmcnt(1)
	v_cmp_ne_u32_e32 vcc, 0, v4
	s_cbranch_vccnz .LBB0_1838
	v_readlane_b32 s4, v244, 2
	v_readlane_b32 s5, v244, 3
	s_load_dwordx2 s[0:1], s[4:5], 0x4
	s_load_dword s3, s[4:5], 0x14
	v_mov_b32_e32 v18, 0
	s_waitcnt lgkmcnt(0)
	s_lshr_b32 s8, s3, 16
	s_and_b32 s3, s3, 0xffff
	s_cmp_lg_u32 s3, 0
	s_cselect_b64 s[4:5], -1, 0
	s_cmp_lg_u64 s[4:5], 0
	s_addc_u32 s0, s0, 0
	s_cmp_lg_u32 s8, 0
	s_cselect_b64 s[4:5], -1, 0
	s_cmp_lg_u64 s[4:5], 0
	s_mul_i32 s3, s0, s33
	s_addc_u32 s0, s1, 0
	s_mul_i32 s3, s3, s0
	s_mov_b32 s4, 1
	s_branch .LBB0_1826
